# seam before the q|k|gate GEMM: the XCD's last arriver issues its invalidate together with the L2 write-back instead of after signalling
# speedup vs baseline: 1.0051x; 1.0051x over previous
; __device__ __forceinline__ unsigned xb_ld(unsigned* p)              { return __hip_atomic_load(p, __ATOMIC_RELAXED, __HIP_MEMORY_SCOPE_AGENT); }
; __device__ __forceinline__ unsigned xb_add(unsigned* p, unsigned v) { return __hip_atomic_fetch_add(p, v, __ATOMIC_RELAXED, __HIP_MEMORY_SCOPE_AGENT); }
; #define XB_SPIN(cond, bar) do { unsigned _sp = 0; while (cond) { __builtin_amdgcn_s_sleep(1); \
;     if ((++_sp & 255u) == 0u) { if (xb_ld(&(bar)[XB_TMO])) break; if (_sp > XB_SPIN_CAP) { atomicAdd(&(bar)[XB_TMO], 1u); break; } } } } while (0)
; __device__ __forceinline__ void xcd_barrier(const XcdBarrier& b) {
;     ...
;         const unsigned old = xb_add(&bar[XB_XSUB(b.x)], 1u);
;         const unsigned gen = old / nloc;
;         if (old + 1u == (gen + 1u) * nloc) {
;             __builtin_amdgcn_fence(__ATOMIC_RELEASE, "agent");
;             asm volatile("s_waitcnt vmcnt(0)" ::: "memory");
;             const unsigned og = xb_add(&bar[XB_TOP], 1u);
;             const unsigned tg = og / nx;
;             if (og + 1u == (tg + 1u) * nx) xb_add(&bar[XB_TOPGEN], 1u);
;             else XB_SPIN(xb_ld(&bar[XB_TOPGEN]) == tg, bar);
;             __builtin_amdgcn_fence(__ATOMIC_ACQUIRE, "agent");
;             xb_add(&bar[XB_XGEN(b.x)], 1u);
;             asm volatile("s_waitcnt vmcnt(0)" ::: "memory");
;         } else {
;             XB_SPIN(xb_ld(&bar[XB_XGEN(b.x)]) == gen, bar);
;             __builtin_amdgcn_fence(__ATOMIC_ACQUIRE, "agent");
;             asm volatile("s_waitcnt vmcnt(0)" ::: "memory");
;         }
.LBB0_441:
	s_waitcnt lgkmcnt(0)
	v_readfirstlane_b32 s98, v2
	v_readfirstlane_b32 s99, v0
	v_mov_b32_e32 v1, 0x20008
	ds_read_b32 v5, v1
	s_lshl_b32 s96, s59, 8
	s_add_u32 s96, s54, s96
	s_addc_u32 s97, s55, 0
	v_mov_b32_e32 v3, 0x1000
	v_mov_b32_e32 v4, 1
	global_atomic_add v3, v3, v4, s[96:97] offset:1024 sc0
	s_waitcnt lgkmcnt(0)
	v_readfirstlane_b32 s100, v5
	s_add_i32 s100, s100, 1
	v_mov_b32_e32 v2, s100
	ds_write_b32 v1, v2
	s_mul_i32 s98, s98, s100
	s_mul_i32 s99, s99, s100
	s_waitcnt vmcnt(0)
	v_readfirstlane_b32 s96, v3
	s_add_i32 s96, s96, 1
	s_cmp_lg_u32 s96, s98
	s_cbranch_scc1 .Lmy_bar_poll_3
	buffer_wbl2 sc1
	buffer_inv sc1
	s_waitcnt vmcnt(0)
	v_mov_b32_e32 v3, 0x3000
	global_atomic_add v3, v4, s[54:55] offset:1024
	s_branch .Lmy_bar_poll3b
.Lmy_bar_poll_3:
	buffer_inv sc1
.Lmy_bar_poll3b:
	v_mov_b32_e32 v3, 0x3000
	s_mov_b32 s97, 0
